# v8 + norm_phase<0> (norm1/2/3): g/scale/shift vectors loaded once per 4-row iteration instead of 3 loads + vmcnt(0) after every store (16 serialized round trips per iteration removed)
# speedup vs baseline: 1.0185x; 1.0114x over previous
.LBB0_675:
	s_or_b64 exec, exec, s[6:7]
	v_ashrrev_i32_e32 v67, 12, v64
	v_mul_i32_i24_e32 v67, 0x2400, v67
	v_cndmask_b32_e64 v86, v186, v67, s[4:5]
	v_readlane_b32 s16, v254, 27
	s_waitcnt vmcnt(11)
	v_mov_b32_e32 v90, v61
	s_waitcnt vmcnt(10)
	v_mov_b32_e32 v91, v57
	v_mov_b32_e32 v84, v60
	v_ashrrev_i32_e32 v87, 31, v86
	v_readlane_b32 s17, v254, 28
	v_mov_b32_e32 v85, v56
	v_pk_mul_f32 v[90:91], v[90:91], v[90:91]
	v_lshl_add_u64 v[94:95], v[86:87], 2, s[16:17]
	v_pk_fma_f32 v[84:85], v[84:85], v[84:85], v[90:91]
	v_mov_b32_e32 v90, v62
	v_mov_b32_e32 v91, v58
	v_lshl_add_u64 v[98:99], v[94:95], 0, s[34:35]
	v_pk_fma_f32 v[84:85], v[90:91], v[90:91], v[84:85]
	v_mov_b32_e32 v90, v63
	v_mov_b32_e32 v91, v59
	s_waitcnt vmcnt(9)
	v_mov_b32_e32 v92, v53
	s_waitcnt vmcnt(8)
	v_mov_b32_e32 v93, v49
	v_lshl_add_u64 v[0:1], v[0:1], 0, v[128:129]
	v_lshl_add_u64 v[86:87], v[98:99], 0, v[128:129]
	v_pk_fma_f32 v[84:85], v[90:91], v[90:91], v[84:85]
	v_mov_b32_e32 v90, v52
	v_mov_b32_e32 v91, v48
	v_pk_mul_f32 v[92:93], v[92:93], v[92:93]
	global_load_dwordx4 v[16:19], v[0:1], off
	global_load_dwordx4 v[8:11], v[0:1], off offset:1024
	global_load_dwordx4 v[4:7], v[0:1], off offset:2048
	s_nop 0
	global_load_dwordx4 v[0:3], v[0:1], off offset:3072
	v_pk_fma_f32 v[100:101], v[90:91], v[90:91], v[92:93]
	v_lshl_add_u64 v[102:103], v[94:95], 0, v[128:129]
	global_load_dwordx4 v[208:211], v[68:69], off
	global_load_dwordx4 v[224:227], v[86:87], off
	global_load_dwordx4 v[240:243], v[102:103], off
	global_load_dwordx4 v[212:215], v[68:69], off offset:1024
	global_load_dwordx4 v[228:231], v[86:87], off offset:1024
	global_load_dwordx4 v[244:247], v[102:103], off offset:1024
	global_load_dwordx4 v[216:219], v[68:69], off offset:2048
	global_load_dwordx4 v[232:235], v[86:87], off offset:2048
	global_load_dwordx4 v[108:111], v[102:103], off offset:2048
	global_load_dwordx4 v[220:223], v[68:69], off offset:3072
	global_load_dwordx4 v[236:239], v[86:87], off offset:3072
	global_load_dwordx4 v[72:75], v[102:103], off offset:3072
	v_mov_b32_e32 v104, v54
	v_mov_b32_e32 v105, v50
	v_pk_fma_f32 v[100:101], v[104:105], v[104:105], v[100:101]
	v_mov_b32_e32 v104, v55
	v_mov_b32_e32 v105, v51
	v_pk_fma_f32 v[100:101], v[104:105], v[104:105], v[100:101]
	v_add_f32_e32 v112, v84, v85
	v_add_f32_e32 v112, v112, v100
	s_waitcnt vmcnt(23)
	v_mov_b32_e32 v104, v45
	s_waitcnt vmcnt(22)
	v_mov_b32_e32 v105, v41
	v_add_f32_e32 v112, v112, v101
	v_mov_b32_e32 v100, v44
	v_mov_b32_e32 v101, v40
	v_pk_mul_f32 v[104:105], v[104:105], v[104:105]
	v_add_f32_dpp v112, v112, v112 quad_perm:[1,0,3,2] row_mask:0xf bank_mask:0xf bound_ctrl:1
	v_pk_fma_f32 v[100:101], v[100:101], v[100:101], v[104:105]
	v_mov_b32_e32 v104, v46
	v_mov_b32_e32 v105, v42
	v_pk_fma_f32 v[100:101], v[104:105], v[104:105], v[100:101]
	v_mov_b32_e32 v104, v47
	v_mov_b32_e32 v105, v43
	s_waitcnt vmcnt(21)
	v_mov_b32_e32 v106, v37
	s_waitcnt vmcnt(20)
	v_mov_b32_e32 v107, v33
	v_add_f32_dpp v112, v112, v112 quad_perm:[2,3,0,1] row_mask:0xf bank_mask:0xf bound_ctrl:1
	v_pk_fma_f32 v[100:101], v[104:105], v[104:105], v[100:101]
	v_mov_b32_e32 v104, v36
	v_mov_b32_e32 v105, v32
	v_pk_mul_f32 v[106:107], v[106:107], v[106:107]
	v_add_f32_dpp v112, v112, v112 row_half_mirror row_mask:0xf bank_mask:0xf bound_ctrl:1
	v_pk_fma_f32 v[104:105], v[104:105], v[104:105], v[106:107]
	v_mov_b32_e32 v106, v38
	v_mov_b32_e32 v107, v34
	v_add_f32_dpp v112, v112, v112 row_mirror row_mask:0xf bank_mask:0xf bound_ctrl:1
	v_pk_fma_f32 v[104:105], v[106:107], v[106:107], v[104:105]
	v_mov_b32_e32 v106, v39
	v_mov_b32_e32 v107, v35
	v_readlane_b32 s4, v112, 0
	v_readlane_b32 s6, v112, 16
	v_readlane_b32 s5, v112, 32
	v_readlane_b32 s7, v112, 48
	v_pk_fma_f32 v[104:105], v[106:107], v[106:107], v[104:105]
	v_add_f32_e32 v112, v100, v101
	v_add_f32_e32 v112, v112, v104
	v_add_f32_e32 v112, v112, v105
	v_mov_b32_e32 v84, s6
	v_mov_b32_e32 v85, s7
	v_add_f32_dpp v112, v112, v112 quad_perm:[1,0,3,2] row_mask:0xf bank_mask:0xf bound_ctrl:1
	v_pk_add_f32 v[84:85], s[4:5], v[84:85]
	v_lshlrev_b64 v[104:105], 11, v[64:65]
	v_add_f32_dpp v112, v112, v112 quad_perm:[2,3,0,1] row_mask:0xf bank_mask:0xf bound_ctrl:1
	v_mov_b32_e32 v107, v84
	v_lshl_add_u64 v[104:105], v[70:71], 0, v[104:105]
	v_add_f32_dpp v112, v112, v112 row_half_mirror row_mask:0xf bank_mask:0xf bound_ctrl:1
	s_waitcnt vmcnt(11)
	s_waitcnt vmcnt(0)
	v_pk_add_f32 v[226:227], v[226:227], 1.0 op_sel_hi:[1,0]
	v_pk_add_f32 v[224:225], v[224:225], 1.0 op_sel_hi:[1,0]
	v_pk_add_f32 v[230:231], v[230:231], 1.0 op_sel_hi:[1,0]
	v_pk_add_f32 v[228:229], v[228:229], 1.0 op_sel_hi:[1,0]
	v_pk_add_f32 v[234:235], v[234:235], 1.0 op_sel_hi:[1,0]
	v_pk_add_f32 v[232:233], v[232:233], 1.0 op_sel_hi:[1,0]
	v_pk_add_f32 v[238:239], v[238:239], 1.0 op_sel_hi:[1,0]
	v_pk_add_f32 v[236:237], v[236:237], 1.0 op_sel_hi:[1,0]
	v_add_f32_dpp v112, v112, v112 row_mirror row_mask:0xf bank_mask:0xf bound_ctrl:1
	s_nop 0
	v_readlane_b32 s6, v112, 16
	v_readlane_b32 s7, v112, 48
	v_readlane_b32 s4, v112, 0
	v_readlane_b32 s5, v112, 32
	v_mov_b32_e32 v100, s6
	v_mov_b32_e32 v101, s7
	v_pk_add_f32 v[100:101], s[4:5], v[100:101]
	s_mov_b32 s6, 0x3a800000
	v_mov_b32_e32 v106, v100
	v_mov_b32_e32 v84, v101
	v_pk_add_f32 v[100:101], v[106:107], v[84:85]
	v_mov_b64_e32 v[84:85], s[38:39]
	v_pk_fma_f32 v[100:101], v[100:101], s[6:7], v[84:85] op_sel_hi:[1,0,0]
	v_mul_f32_e32 v65, 0x4b800000, v101
	v_cmp_gt_f32_e64 s[4:5], s20, v101
	s_nop 1
	v_cndmask_b32_e64 v65, v101, v65, s[4:5]
	v_rsq_f32_e32 v65, v65
	s_nop 0
	v_mul_f32_e32 v188, 0x45800000, v65
	v_cndmask_b32_e64 v106, v65, v188, s[4:5]
	v_pk_mul_f32 v[62:63], v[62:63], v[106:107] op_sel_hi:[1,0]
	v_pk_mul_f32 v[60:61], v[60:61], v[106:107] op_sel_hi:[1,0]
	v_pk_mul_f32 v[62:63], v[62:63], v[210:211]
	v_pk_mul_f32 v[60:61], v[60:61], v[208:209]
	v_pk_fma_f32 v[62:63], v[62:63], v[226:227], v[242:243]
	v_pk_fma_f32 v[60:61], v[60:61], v[224:225], v[240:241]
	v_cvt_pk_bf16_f32 v60, v60, v61
	v_cvt_pk_bf16_f32 v61, v62, v63
	global_store_dwordx2 v[104:105], v[60:61], off
	s_nop 0
	s_nop 0
	v_pk_mul_f32 v[58:59], v[58:59], v[106:107] op_sel_hi:[1,0]
	v_pk_mul_f32 v[56:57], v[56:57], v[106:107] op_sel_hi:[1,0]
	v_pk_mul_f32 v[54:55], v[54:55], v[106:107] op_sel_hi:[1,0]
	v_pk_mul_f32 v[52:53], v[52:53], v[106:107] op_sel_hi:[1,0]
	v_pk_mul_f32 v[50:51], v[50:51], v[106:107] op_sel_hi:[1,0]
	v_pk_mul_f32 v[48:49], v[48:49], v[106:107] op_sel_hi:[1,0]
	v_pk_mul_f32 v[56:57], v[56:57], v[212:213]
	v_pk_mul_f32 v[58:59], v[58:59], v[214:215]
	v_pk_fma_f32 v[58:59], v[58:59], v[230:231], v[246:247]
	v_pk_fma_f32 v[56:57], v[56:57], v[228:229], v[244:245]
	v_cvt_pk_bf16_f32 v56, v56, v57
	v_cvt_pk_bf16_f32 v57, v58, v59
	global_store_dwordx2 v[104:105], v[56:57], off offset:512
	s_nop 0
	s_nop 0
	v_pk_mul_f32 v[52:53], v[52:53], v[216:217]
	v_pk_mul_f32 v[54:55], v[54:55], v[218:219]
	v_pk_fma_f32 v[54:55], v[54:55], v[234:235], v[110:111]
	v_pk_fma_f32 v[52:53], v[52:53], v[232:233], v[108:109]
	v_cvt_pk_bf16_f32 v52, v52, v53
	v_cvt_pk_bf16_f32 v53, v54, v55
	global_store_dwordx2 v[104:105], v[52:53], off offset:1024
	s_nop 0
	s_nop 0
	v_cndmask_b32_e64 v86, v186, v67, s[2:3]
	v_ashrrev_i32_e32 v87, 31, v86
	v_lshl_add_u64 v[86:87], v[86:87], 2, s[16:17]
	v_lshl_add_u64 v[88:89], v[86:87], 0, s[34:35]
	v_cmp_gt_f32_e64 s[2:3], s20, v100
	v_pk_mul_f32 v[48:49], v[48:49], v[220:221]
	v_pk_mul_f32 v[50:51], v[50:51], v[222:223]
	v_pk_fma_f32 v[50:51], v[50:51], v[238:239], v[74:75]
	v_pk_fma_f32 v[48:49], v[48:49], v[236:237], v[72:73]
	v_lshl_add_u64 v[52:53], v[88:89], 0, v[128:129]
	v_cvt_pk_bf16_f32 v48, v48, v49
	v_cvt_pk_bf16_f32 v49, v50, v51
	global_store_dwordx2 v[104:105], v[48:49], off offset:1536
	v_lshl_add_u64 v[60:61], v[86:87], 0, v[128:129]
	v_mul_f32_e32 v62, 0x4b800000, v100
	v_cndmask_b32_e64 v62, v100, v62, s[2:3]
	v_rsq_f32_e32 v65, v62
	v_lshlrev_b64 v[62:63], 11, v[82:83]
	v_lshl_add_u64 v[62:63], v[70:71], 0, v[62:63]
	v_mov_b32_e32 v86, v23
	v_mul_f32_e32 v82, 0x45800000, v65
	v_cndmask_b32_e64 v82, v65, v82, s[2:3]
	v_pk_mul_f32 v[46:47], v[46:47], v[82:83] op_sel_hi:[1,0]
	v_pk_mul_f32 v[44:45], v[44:45], v[82:83] op_sel_hi:[1,0]
	v_pk_mul_f32 v[42:43], v[42:43], v[82:83] op_sel_hi:[1,0]
	v_pk_mul_f32 v[40:41], v[40:41], v[82:83] op_sel_hi:[1,0]
	v_pk_mul_f32 v[38:39], v[38:39], v[82:83] op_sel_hi:[1,0]
	v_pk_mul_f32 v[36:37], v[36:37], v[82:83] op_sel_hi:[1,0]
	v_pk_mul_f32 v[34:35], v[34:35], v[82:83] op_sel_hi:[1,0]
	v_pk_mul_f32 v[32:33], v[32:33], v[82:83] op_sel_hi:[1,0]
	v_mov_b32_e32 v87, v15
	v_mov_b32_e32 v82, v7
	v_mov_b32_e32 v83, v3
	v_pk_mul_f32 v[44:45], v[44:45], v[208:209]
	v_pk_mul_f32 v[46:47], v[46:47], v[210:211]
	v_pk_fma_f32 v[46:47], v[46:47], v[226:227], v[242:243]
	v_pk_fma_f32 v[44:45], v[44:45], v[224:225], v[240:241]
	v_cvt_pk_bf16_f32 v44, v44, v45
	v_cvt_pk_bf16_f32 v45, v46, v47
	global_store_dwordx2 v[62:63], v[44:45], off
	s_nop 0
	s_nop 0
	v_mov_b32_e32 v58, v21
	v_mov_b32_e32 v59, v13
	v_mov_b32_e32 v56, v20
	v_mov_b32_e32 v57, v12
	v_pk_mul_f32 v[40:41], v[40:41], v[212:213]
	v_pk_mul_f32 v[42:43], v[42:43], v[214:215]
	v_pk_fma_f32 v[42:43], v[42:43], v[230:231], v[246:247]
	v_pk_fma_f32 v[40:41], v[40:41], v[228:229], v[244:245]
	v_cvt_pk_bf16_f32 v40, v40, v41
	v_cvt_pk_bf16_f32 v41, v42, v43
	global_store_dwordx2 v[62:63], v[40:41], off offset:512
	s_nop 0
	s_nop 0
	v_mov_b32_e32 v52, v30
	v_mov_b32_e32 v53, v26
	v_mov_b32_e32 v54, v31
	v_mov_b32_e32 v55, v27
	v_pk_mul_f32 v[36:37], v[36:37], v[216:217]
	v_pk_mul_f32 v[38:39], v[38:39], v[218:219]
	v_pk_fma_f32 v[38:39], v[38:39], v[234:235], v[110:111]
	v_pk_fma_f32 v[36:37], v[36:37], v[232:233], v[108:109]
	v_cvt_pk_bf16_f32 v36, v36, v37
	v_cvt_pk_bf16_f32 v37, v38, v39
	global_store_dwordx2 v[62:63], v[36:37], off offset:1024
	s_nop 0
	s_nop 0
	v_cndmask_b32_e64 v88, v186, v67, s[0:1]
	v_ashrrev_i32_e32 v89, 31, v88
	v_lshl_add_u64 v[88:89], v[88:89], 2, s[16:17]
	v_lshl_add_u64 v[90:91], v[88:89], 0, s[34:35]
	v_lshl_add_u64 v[92:93], v[90:91], 0, v[128:129]
	v_mov_b32_e32 v50, v29
	v_mov_b32_e32 v51, v25
	v_mov_b32_e32 v48, v28
	v_mov_b32_e32 v49, v24
	v_mov_b32_e32 v60, v22
	v_mov_b32_e32 v61, v14
	v_pk_mul_f32 v[32:33], v[32:33], v[220:221]
	v_pk_mul_f32 v[34:35], v[34:35], v[222:223]
	v_pk_fma_f32 v[34:35], v[34:35], v[238:239], v[74:75]
	v_pk_fma_f32 v[32:33], v[32:33], v[236:237], v[72:73]
	v_lshl_add_u64 v[46:47], v[88:89], 0, v[128:129]
	v_cvt_pk_bf16_f32 v32, v32, v33
	v_cvt_pk_bf16_f32 v33, v34, v35
	global_store_dwordx2 v[62:63], v[32:33], off offset:1536
	v_pk_mul_f32 v[44:45], v[50:51], v[50:51]
	v_pk_mul_f32 v[50:51], v[58:59], v[58:59]
	v_pk_fma_f32 v[44:45], v[48:49], v[48:49], v[44:45]
	v_pk_fma_f32 v[48:49], v[56:57], v[56:57], v[50:51]
	v_pk_fma_f32 v[44:45], v[52:53], v[52:53], v[44:45]
	v_pk_fma_f32 v[48:49], v[60:61], v[60:61], v[48:49]
	v_pk_fma_f32 v[44:45], v[54:55], v[54:55], v[44:45]
	v_pk_fma_f32 v[48:49], v[86:87], v[86:87], v[48:49]
	v_add_f32_e32 v44, v44, v45
	v_add_f32_e32 v44, v44, v48
	v_add_f32_e32 v44, v44, v49
	v_mov_b32_e32 v52, v17
	v_mov_b32_e32 v53, v9
	v_add_f32_dpp v44, v44, v44 quad_perm:[1,0,3,2] row_mask:0xf bank_mask:0xf bound_ctrl:1
	v_mov_b32_e32 v50, v16
	v_mov_b32_e32 v51, v8
	v_add_f32_dpp v44, v44, v44 quad_perm:[2,3,0,1] row_mask:0xf bank_mask:0xf bound_ctrl:1
	v_mov_b32_e32 v60, v5
	v_mov_b32_e32 v61, v1
	v_add_f32_dpp v44, v44, v44 row_half_mirror row_mask:0xf bank_mask:0xf bound_ctrl:1
	v_pk_mul_f32 v[52:53], v[52:53], v[52:53]
	v_mov_b32_e32 v54, v18
	v_add_f32_dpp v44, v44, v44 row_mirror row_mask:0xf bank_mask:0xf bound_ctrl:1
	v_mov_b32_e32 v55, v10
	v_readlane_b32 s2, v44, 16
	v_readlane_b32 s3, v44, 48
	v_mov_b32_e32 v58, v4
	v_mov_b32_e32 v59, v0
	v_pk_mul_f32 v[60:61], v[60:61], v[60:61]
	v_pk_fma_f32 v[50:51], v[50:51], v[50:51], v[52:53]
	v_readlane_b32 s0, v44, 0
	v_readlane_b32 s1, v44, 32
	v_mov_b32_e32 v44, s2
	v_mov_b32_e32 v45, s3
	v_mov_b32_e32 v56, v19
	v_mov_b32_e32 v57, v11
	v_mov_b32_e32 v62, v6
	v_mov_b32_e32 v63, v2
	v_pk_fma_f32 v[52:53], v[58:59], v[58:59], v[60:61]
	v_pk_fma_f32 v[50:51], v[54:55], v[54:55], v[50:51]
	v_pk_add_f32 v[44:45], s[0:1], v[44:45]
	v_pk_fma_f32 v[52:53], v[62:63], v[62:63], v[52:53]
	v_pk_fma_f32 v[50:51], v[56:57], v[56:57], v[50:51]
	v_mov_b32_e32 v49, v44
	v_pk_fma_f32 v[52:53], v[82:83], v[82:83], v[52:53]
	v_add_f32_e32 v44, v50, v51
	v_add_f32_e32 v44, v44, v52
	v_add_f32_e32 v44, v44, v53
	s_nop 1
	v_add_f32_dpp v44, v44, v44 quad_perm:[1,0,3,2] row_mask:0xf bank_mask:0xf bound_ctrl:1
	s_nop 0
	s_nop 0
	v_add_f32_dpp v44, v44, v44 quad_perm:[2,3,0,1] row_mask:0xf bank_mask:0xf bound_ctrl:1
	s_nop 1
	v_add_f32_dpp v44, v44, v44 row_half_mirror row_mask:0xf bank_mask:0xf bound_ctrl:1
	s_nop 1
	v_add_f32_dpp v44, v44, v44 row_mirror row_mask:0xf bank_mask:0xf bound_ctrl:1
	s_nop 0
	v_readlane_b32 s2, v44, 16
	v_readlane_b32 s3, v44, 48
	v_readlane_b32 s0, v44, 0
	v_readlane_b32 s1, v44, 32
	v_mov_b32_e32 v50, s2
	v_mov_b32_e32 v51, s3
	v_pk_add_f32 v[50:51], s[0:1], v[50:51]
	s_nop 0
	v_mov_b32_e32 v48, v50
	v_mov_b32_e32 v44, v51
	v_pk_add_f32 v[44:45], v[48:49], v[44:45]
	s_nop 0
	v_pk_fma_f32 v[44:45], v[44:45], s[6:7], v[84:85] op_sel_hi:[1,0,0]
	s_nop 0
	v_mul_f32_e32 v48, 0x4b800000, v45
	v_cmp_gt_f32_e64 s[0:1], s20, v45
	s_nop 1
	v_cndmask_b32_e64 v45, v45, v48, s[0:1]
	v_rsq_f32_e32 v45, v45
	v_lshlrev_b64 v[48:49], 11, v[80:81]
	v_lshl_add_u64 v[48:49], v[70:71], 0, v[48:49]
	v_mul_f32_e32 v50, 0x45800000, v45
	v_cndmask_b32_e64 v50, v45, v50, s[0:1]
	v_pk_mul_f32 v[30:31], v[30:31], v[50:51] op_sel_hi:[1,0]
	v_pk_mul_f32 v[28:29], v[28:29], v[50:51] op_sel_hi:[1,0]
	v_pk_mul_f32 v[30:31], v[30:31], v[210:211]
	v_pk_mul_f32 v[28:29], v[28:29], v[208:209]
	v_pk_fma_f32 v[30:31], v[30:31], v[226:227], v[242:243]
	v_pk_fma_f32 v[28:29], v[28:29], v[224:225], v[240:241]
	v_cvt_pk_bf16_f32 v28, v28, v29
	v_cvt_pk_bf16_f32 v29, v30, v31
	global_store_dwordx2 v[48:49], v[28:29], off
	s_nop 0
	s_nop 0
	v_pk_mul_f32 v[26:27], v[26:27], v[50:51] op_sel_hi:[1,0]
	v_pk_mul_f32 v[24:25], v[24:25], v[50:51] op_sel_hi:[1,0]
	v_pk_mul_f32 v[22:23], v[22:23], v[50:51] op_sel_hi:[1,0]
	v_pk_mul_f32 v[20:21], v[20:21], v[50:51] op_sel_hi:[1,0]
	v_pk_mul_f32 v[14:15], v[14:15], v[50:51] op_sel_hi:[1,0]
	v_pk_mul_f32 v[12:13], v[12:13], v[50:51] op_sel_hi:[1,0]
	v_readlane_b32 s0, v252, 26
	v_pk_mul_f32 v[24:25], v[24:25], v[212:213]
	v_pk_mul_f32 v[26:27], v[26:27], v[214:215]
	v_pk_fma_f32 v[26:27], v[26:27], v[230:231], v[246:247]
	v_pk_fma_f32 v[24:25], v[24:25], v[228:229], v[244:245]
	v_cvt_pk_bf16_f32 v24, v24, v25
	v_cvt_pk_bf16_f32 v25, v26, v27
	global_store_dwordx2 v[48:49], v[24:25], off offset:512
	s_nop 0
	s_nop 0
	v_pk_mul_f32 v[20:21], v[20:21], v[216:217]
	v_pk_mul_f32 v[22:23], v[22:23], v[218:219]
	v_pk_fma_f32 v[22:23], v[22:23], v[234:235], v[110:111]
	v_pk_fma_f32 v[20:21], v[20:21], v[232:233], v[108:109]
	v_cvt_pk_bf16_f32 v20, v20, v21
	v_cvt_pk_bf16_f32 v21, v22, v23
	global_store_dwordx2 v[48:49], v[20:21], off offset:1024
	s_nop 0
	s_nop 0
	v_cndmask_b32_e32 v32, v186, v67, vcc
	v_ashrrev_i32_e32 v33, 31, v32
	v_lshl_add_u64 v[32:33], v[32:33], 2, s[16:17]
	v_lshl_add_u64 v[34:35], v[32:33], 0, s[34:35]
	v_cmp_gt_f32_e32 vcc, s20, v44
	v_pk_mul_f32 v[12:13], v[12:13], v[220:221]
	v_pk_mul_f32 v[14:15], v[14:15], v[222:223]
	v_pk_fma_f32 v[14:15], v[14:15], v[238:239], v[74:75]
	v_pk_fma_f32 v[12:13], v[12:13], v[236:237], v[72:73]
	v_lshl_add_u64 v[20:21], v[34:35], 0, v[128:129]
	v_cvt_pk_bf16_f32 v12, v12, v13
	v_cvt_pk_bf16_f32 v13, v14, v15
	global_store_dwordx2 v[48:49], v[12:13], off offset:1536
	v_lshl_add_u64 v[28:29], v[32:33], 0, v[128:129]
	v_mul_f32_e32 v30, 0x4b800000, v44
	v_cndmask_b32_e32 v30, v44, v30, vcc
	v_rsq_f32_e32 v32, v30
	v_lshlrev_b64 v[30:31], 11, v[78:79]
	v_lshl_add_u64 v[30:31], v[70:71], 0, v[30:31]
	v_mul_f32_e32 v33, 0x45800000, v32
	v_cndmask_b32_e32 v32, v32, v33, vcc
	v_pk_mul_f32 v[18:19], v[18:19], v[32:33] op_sel_hi:[1,0]
	v_pk_mul_f32 v[16:17], v[16:17], v[32:33] op_sel_hi:[1,0]
	v_pk_mul_f32 v[10:11], v[10:11], v[32:33] op_sel_hi:[1,0]
	v_pk_mul_f32 v[8:9], v[8:9], v[32:33] op_sel_hi:[1,0]
	v_pk_mul_f32 v[6:7], v[6:7], v[32:33] op_sel_hi:[1,0]
	v_pk_mul_f32 v[4:5], v[4:5], v[32:33] op_sel_hi:[1,0]
	v_pk_mul_f32 v[2:3], v[2:3], v[32:33] op_sel_hi:[1,0]
	v_pk_mul_f32 v[0:1], v[0:1], v[32:33] op_sel_hi:[1,0]
	v_pk_mul_f32 v[12:13], v[16:17], v[208:209]
	v_pk_mul_f32 v[14:15], v[18:19], v[210:211]
	v_pk_fma_f32 v[14:15], v[14:15], v[226:227], v[242:243]
	v_pk_fma_f32 v[12:13], v[12:13], v[224:225], v[240:241]
	v_cvt_pk_bf16_f32 v12, v12, v13
	v_cvt_pk_bf16_f32 v13, v14, v15
	global_store_dwordx2 v[30:31], v[12:13], off
	s_nop 0
	s_nop 0
	v_pk_mul_f32 v[8:9], v[8:9], v[212:213]
	v_pk_mul_f32 v[10:11], v[10:11], v[214:215]
	v_pk_fma_f32 v[10:11], v[10:11], v[230:231], v[246:247]
	v_pk_fma_f32 v[8:9], v[8:9], v[228:229], v[244:245]
	v_cvt_pk_bf16_f32 v8, v8, v9
	v_cvt_pk_bf16_f32 v9, v10, v11
	global_store_dwordx2 v[30:31], v[8:9], off offset:512
	s_nop 0
	s_nop 0
	v_pk_mul_f32 v[4:5], v[4:5], v[216:217]
	v_pk_mul_f32 v[6:7], v[6:7], v[218:219]
	v_pk_fma_f32 v[6:7], v[6:7], v[234:235], v[110:111]
	v_pk_fma_f32 v[4:5], v[4:5], v[232:233], v[108:109]
	v_cvt_pk_bf16_f32 v4, v4, v5
	v_cvt_pk_bf16_f32 v5, v6, v7
	global_store_dwordx2 v[30:31], v[4:5], off offset:1024
	s_nop 0
	s_nop 0
	v_pk_mul_f32 v[0:1], v[0:1], v[220:221]
	v_pk_mul_f32 v[2:3], v[2:3], v[222:223]
	v_pk_fma_f32 v[2:3], v[2:3], v[238:239], v[74:75]
	v_pk_fma_f32 v[0:1], v[0:1], v[236:237], v[72:73]
	s_nop 0
	v_cvt_pk_bf16_f32 v0, v0, v1
	v_cvt_pk_bf16_f32 v1, v2, v3
	global_store_dwordx2 v[30:31], v[0:1], off offset:1536
	s_nop 0
	v_lshl_add_u32 v64, s0, 4, v64
	s_mov_b32 s0, 0x87ff
	v_cmp_lt_i32_e32 vcc, s0, v64
	s_or_b64 s[14:15], vcc, s[14:15]
	s_andn2_b64 exec, exec, s[14:15]
	s_cbranch_execz .LBB0_680

.LBB0_876:
	s_or_b64 exec, exec, s[8:9]
	v_ashrrev_i32_e32 v67, 12, v64
	v_mul_i32_i24_e32 v67, 0x2400, v67
	v_cndmask_b32_e64 v86, v186, v67, s[6:7]
	v_readlane_b32 s18, v254, 27
	s_waitcnt vmcnt(11)
	v_mov_b32_e32 v92, v61
	s_waitcnt vmcnt(10)
	v_mov_b32_e32 v93, v57
	v_mov_b32_e32 v84, v60
	v_mov_b32_e32 v85, v56
	v_ashrrev_i32_e32 v87, 31, v86
	v_readlane_b32 s19, v254, 28
	v_pk_mul_f32 v[92:93], v[92:93], v[92:93]
	s_mov_b64 s[14:15], 0x4000
	v_lshl_add_u64 v[90:91], v[86:87], 2, s[18:19]
	v_pk_fma_f32 v[84:85], v[84:85], v[84:85], v[92:93]
	v_mov_b32_e32 v92, v62
	v_mov_b32_e32 v93, v58
	v_lshl_add_u64 v[98:99], v[90:91], 0, s[14:15]
	v_pk_fma_f32 v[84:85], v[92:93], v[92:93], v[84:85]
	v_mov_b32_e32 v92, v63
	v_mov_b32_e32 v93, v59
	s_waitcnt vmcnt(9)
	v_mov_b32_e32 v94, v53
	s_waitcnt vmcnt(8)
	v_mov_b32_e32 v95, v49
	s_mov_b64 s[16:17], 0x3000
	v_lshl_add_u64 v[0:1], v[0:1], 0, v[128:129]
	v_lshl_add_u64 v[86:87], v[98:99], 0, v[128:129]
	v_pk_fma_f32 v[84:85], v[92:93], v[92:93], v[84:85]
	v_mov_b32_e32 v92, v52
	v_mov_b32_e32 v93, v48
	v_pk_mul_f32 v[94:95], v[94:95], v[94:95]
	v_lshl_add_u64 v[102:103], v[90:91], 0, s[16:17]
	global_load_dwordx4 v[16:19], v[0:1], off
	global_load_dwordx4 v[12:15], v[0:1], off offset:1024
	global_load_dwordx4 v[8:11], v[0:1], off offset:2048
	s_nop 0
	global_load_dwordx4 v[0:3], v[0:1], off offset:3072
	v_pk_fma_f32 v[100:101], v[92:93], v[92:93], v[94:95]
	v_lshl_add_u64 v[94:95], v[102:103], 0, v[128:129]
	v_mov_b32_e32 v104, v54
	global_load_dwordx4 v[208:211], v[68:69], off
	global_load_dwordx4 v[224:227], v[86:87], off
	global_load_dwordx4 v[240:243], v[94:95], off
	global_load_dwordx4 v[212:215], v[68:69], off offset:1024
	global_load_dwordx4 v[228:231], v[86:87], off offset:1024
	global_load_dwordx4 v[244:247], v[94:95], off offset:1024
	global_load_dwordx4 v[216:219], v[68:69], off offset:2048
	global_load_dwordx4 v[232:235], v[86:87], off offset:2048
	global_load_dwordx4 v[108:111], v[94:95], off offset:2048
	global_load_dwordx4 v[220:223], v[68:69], off offset:3072
	global_load_dwordx4 v[236:239], v[86:87], off offset:3072
	global_load_dwordx4 v[72:75], v[94:95], off offset:3072
	v_mov_b32_e32 v105, v50
	v_pk_fma_f32 v[100:101], v[104:105], v[104:105], v[100:101]
	v_mov_b32_e32 v104, v55
	v_mov_b32_e32 v105, v51
	v_pk_fma_f32 v[100:101], v[104:105], v[104:105], v[100:101]
	v_add_f32_e32 v112, v84, v85
	v_add_f32_e32 v112, v112, v100
	s_waitcnt vmcnt(23)
	v_mov_b32_e32 v104, v45
	s_waitcnt vmcnt(22)
	v_mov_b32_e32 v105, v41
	v_add_f32_e32 v112, v112, v101
	v_mov_b32_e32 v100, v44
	v_mov_b32_e32 v101, v40
	v_pk_mul_f32 v[104:105], v[104:105], v[104:105]
	v_add_f32_dpp v112, v112, v112 quad_perm:[1,0,3,2] row_mask:0xf bank_mask:0xf bound_ctrl:1
	v_pk_fma_f32 v[100:101], v[100:101], v[100:101], v[104:105]
	v_mov_b32_e32 v104, v46
	v_mov_b32_e32 v105, v42
	v_pk_fma_f32 v[100:101], v[104:105], v[104:105], v[100:101]
	v_mov_b32_e32 v104, v47
	v_mov_b32_e32 v105, v43
	s_waitcnt vmcnt(21)
	v_mov_b32_e32 v106, v37
	s_waitcnt vmcnt(20)
	v_mov_b32_e32 v107, v33
	v_add_f32_dpp v112, v112, v112 quad_perm:[2,3,0,1] row_mask:0xf bank_mask:0xf bound_ctrl:1
	v_pk_fma_f32 v[100:101], v[104:105], v[104:105], v[100:101]
	v_mov_b32_e32 v104, v36
	v_mov_b32_e32 v105, v32
	v_pk_mul_f32 v[106:107], v[106:107], v[106:107]
	v_add_f32_dpp v112, v112, v112 row_half_mirror row_mask:0xf bank_mask:0xf bound_ctrl:1
	v_pk_fma_f32 v[104:105], v[104:105], v[104:105], v[106:107]
	v_mov_b32_e32 v106, v38
	v_mov_b32_e32 v107, v34
	v_add_f32_dpp v112, v112, v112 row_mirror row_mask:0xf bank_mask:0xf bound_ctrl:1
	v_pk_fma_f32 v[104:105], v[106:107], v[106:107], v[104:105]
	v_mov_b32_e32 v106, v39
	v_mov_b32_e32 v107, v35
	v_readlane_b32 s6, v112, 0
	v_readlane_b32 s8, v112, 16
	v_readlane_b32 s7, v112, 32
	v_readlane_b32 s9, v112, 48
	v_pk_fma_f32 v[104:105], v[106:107], v[106:107], v[104:105]
	v_add_f32_e32 v112, v100, v101
	v_add_f32_e32 v112, v112, v104
	v_add_f32_e32 v112, v112, v105
	v_mov_b32_e32 v84, s8
	v_mov_b32_e32 v85, s9
	v_add_f32_dpp v112, v112, v112 quad_perm:[1,0,3,2] row_mask:0xf bank_mask:0xf bound_ctrl:1
	v_pk_add_f32 v[84:85], s[6:7], v[84:85]
	s_mov_b32 s12, 0x3a800000
	v_add_f32_dpp v112, v112, v112 quad_perm:[2,3,0,1] row_mask:0xf bank_mask:0xf bound_ctrl:1
	v_mov_b32_e32 v107, v84
	v_lshlrev_b64 v[104:105], 11, v[64:65]
	v_add_f32_dpp v112, v112, v112 row_half_mirror row_mask:0xf bank_mask:0xf bound_ctrl:1
	v_lshl_add_u64 v[104:105], v[70:71], 0, v[104:105]
	s_nop 0
	v_add_f32_dpp v112, v112, v112 row_mirror row_mask:0xf bank_mask:0xf bound_ctrl:1
	s_waitcnt vmcnt(11)
	s_waitcnt vmcnt(0)
	v_pk_add_f32 v[226:227], v[226:227], 1.0 op_sel_hi:[1,0]
	v_pk_add_f32 v[224:225], v[224:225], 1.0 op_sel_hi:[1,0]
	v_pk_add_f32 v[230:231], v[230:231], 1.0 op_sel_hi:[1,0]
	v_pk_add_f32 v[228:229], v[228:229], 1.0 op_sel_hi:[1,0]
	v_pk_add_f32 v[234:235], v[234:235], 1.0 op_sel_hi:[1,0]
	v_pk_add_f32 v[232:233], v[232:233], 1.0 op_sel_hi:[1,0]
	v_pk_add_f32 v[238:239], v[238:239], 1.0 op_sel_hi:[1,0]
	v_pk_add_f32 v[236:237], v[236:237], 1.0 op_sel_hi:[1,0]
	v_readlane_b32 s8, v112, 16
	v_readlane_b32 s9, v112, 48
	v_readlane_b32 s6, v112, 0
	v_readlane_b32 s7, v112, 32
	v_mov_b32_e32 v100, s8
	v_mov_b32_e32 v101, s9
	v_pk_add_f32 v[100:101], s[6:7], v[100:101]
	s_mov_b32 s6, 0x358637bd
	v_mov_b32_e32 v106, v100
	v_mov_b32_e32 v84, v101
	v_pk_add_f32 v[100:101], v[106:107], v[84:85]
	v_mov_b64_e32 v[84:85], s[6:7]
	v_pk_fma_f32 v[100:101], v[100:101], s[12:13], v[84:85] op_sel_hi:[1,0,0]
	s_mov_b32 s8, 0x800000
	v_mul_f32_e32 v65, 0x4b800000, v101
	v_cmp_gt_f32_e64 s[6:7], s8, v101
	s_nop 1
	v_cndmask_b32_e64 v65, v101, v65, s[6:7]
	v_rsq_f32_e32 v65, v65
	s_nop 0
	v_mul_f32_e32 v188, 0x45800000, v65
	v_cndmask_b32_e64 v106, v65, v188, s[6:7]
	v_pk_mul_f32 v[62:63], v[62:63], v[106:107] op_sel_hi:[1,0]
	v_pk_mul_f32 v[60:61], v[60:61], v[106:107] op_sel_hi:[1,0]
	v_pk_mul_f32 v[62:63], v[62:63], v[210:211]
	v_pk_mul_f32 v[60:61], v[60:61], v[208:209]
	v_pk_fma_f32 v[62:63], v[62:63], v[226:227], v[242:243]
	v_pk_fma_f32 v[60:61], v[60:61], v[224:225], v[240:241]
	v_cvt_pk_bf16_f32 v60, v60, v61
	v_cvt_pk_bf16_f32 v61, v62, v63
	global_store_dwordx2 v[104:105], v[60:61], off
	v_pk_mul_f32 v[58:59], v[58:59], v[106:107] op_sel_hi:[1,0]
	v_pk_mul_f32 v[56:57], v[56:57], v[106:107] op_sel_hi:[1,0]
	v_pk_mul_f32 v[54:55], v[54:55], v[106:107] op_sel_hi:[1,0]
	v_pk_mul_f32 v[52:53], v[52:53], v[106:107] op_sel_hi:[1,0]
	v_pk_mul_f32 v[50:51], v[50:51], v[106:107] op_sel_hi:[1,0]
	v_pk_mul_f32 v[48:49], v[48:49], v[106:107] op_sel_hi:[1,0]
	v_pk_mul_f32 v[56:57], v[56:57], v[212:213]
	v_pk_mul_f32 v[58:59], v[58:59], v[214:215]
	v_pk_fma_f32 v[58:59], v[58:59], v[230:231], v[246:247]
	v_pk_fma_f32 v[56:57], v[56:57], v[228:229], v[244:245]
	v_cvt_pk_bf16_f32 v56, v56, v57
	v_cvt_pk_bf16_f32 v57, v58, v59
	global_store_dwordx2 v[104:105], v[56:57], off offset:512
	v_pk_mul_f32 v[52:53], v[52:53], v[216:217]
	v_pk_mul_f32 v[54:55], v[54:55], v[218:219]
	v_pk_fma_f32 v[54:55], v[54:55], v[234:235], v[110:111]
	v_pk_fma_f32 v[52:53], v[52:53], v[232:233], v[108:109]
	v_cvt_pk_bf16_f32 v52, v52, v53
	v_cvt_pk_bf16_f32 v53, v54, v55
	global_store_dwordx2 v[104:105], v[52:53], off offset:1024
	v_cndmask_b32_e64 v86, v186, v67, s[4:5]
	v_ashrrev_i32_e32 v87, 31, v86
	v_lshl_add_u64 v[86:87], v[86:87], 2, s[18:19]
	v_lshl_add_u64 v[88:89], v[86:87], 0, s[14:15]
	v_lshl_add_u64 v[86:87], v[86:87], 0, s[16:17]
	v_cmp_gt_f32_e64 s[4:5], s8, v100
	v_pk_mul_f32 v[48:49], v[48:49], v[220:221]
	v_pk_mul_f32 v[50:51], v[50:51], v[222:223]
	v_pk_fma_f32 v[50:51], v[50:51], v[238:239], v[74:75]
	v_pk_fma_f32 v[48:49], v[48:49], v[236:237], v[72:73]
	v_lshl_add_u64 v[52:53], v[88:89], 0, v[128:129]
	v_cvt_pk_bf16_f32 v48, v48, v49
	v_cvt_pk_bf16_f32 v49, v50, v51
	global_store_dwordx2 v[104:105], v[48:49], off offset:1536
	v_lshl_add_u64 v[56:57], v[86:87], 0, v[128:129]
	v_mul_f32_e32 v60, 0x4b800000, v100
	v_cndmask_b32_e64 v60, v100, v60, s[4:5]
	v_rsq_f32_e32 v62, v60
	v_lshlrev_b64 v[60:61], 11, v[82:83]
	v_lshl_add_u64 v[60:61], v[70:71], 0, v[60:61]
	v_mov_b32_e32 v82, v22
	v_mul_f32_e32 v63, 0x45800000, v62
	v_cndmask_b32_e64 v62, v62, v63, s[4:5]
	v_pk_mul_f32 v[46:47], v[46:47], v[62:63] op_sel_hi:[1,0]
	v_pk_mul_f32 v[44:45], v[44:45], v[62:63] op_sel_hi:[1,0]
	v_pk_mul_f32 v[42:43], v[42:43], v[62:63] op_sel_hi:[1,0]
	v_pk_mul_f32 v[40:41], v[40:41], v[62:63] op_sel_hi:[1,0]
	v_pk_mul_f32 v[38:39], v[38:39], v[62:63] op_sel_hi:[1,0]
	v_pk_mul_f32 v[36:37], v[36:37], v[62:63] op_sel_hi:[1,0]
	v_pk_mul_f32 v[34:35], v[34:35], v[62:63] op_sel_hi:[1,0]
	v_pk_mul_f32 v[32:33], v[32:33], v[62:63] op_sel_hi:[1,0]
	v_mov_b32_e32 v83, v6
	v_mov_b32_e32 v62, v10
	v_mov_b32_e32 v63, v2
	v_pk_mul_f32 v[44:45], v[44:45], v[208:209]
	v_pk_mul_f32 v[46:47], v[46:47], v[210:211]
	v_pk_fma_f32 v[46:47], v[46:47], v[226:227], v[242:243]
	v_pk_fma_f32 v[44:45], v[44:45], v[224:225], v[240:241]
	v_cvt_pk_bf16_f32 v44, v44, v45
	v_cvt_pk_bf16_f32 v45, v46, v47
	global_store_dwordx2 v[60:61], v[44:45], off
	v_mov_b32_e32 v58, v21
	v_mov_b32_e32 v59, v5
	v_mov_b32_e32 v56, v20
	v_mov_b32_e32 v57, v4
	v_pk_mul_f32 v[40:41], v[40:41], v[212:213]
	v_pk_mul_f32 v[42:43], v[42:43], v[214:215]
	v_pk_fma_f32 v[42:43], v[42:43], v[230:231], v[246:247]
	v_pk_fma_f32 v[40:41], v[40:41], v[228:229], v[244:245]
	v_cvt_pk_bf16_f32 v40, v40, v41
	v_cvt_pk_bf16_f32 v41, v42, v43
	global_store_dwordx2 v[60:61], v[40:41], off offset:512
	v_mov_b32_e32 v52, v30
	v_mov_b32_e32 v53, v26
	v_mov_b32_e32 v54, v31
	v_mov_b32_e32 v55, v27
	v_pk_mul_f32 v[36:37], v[36:37], v[216:217]
	v_pk_mul_f32 v[38:39], v[38:39], v[218:219]
	v_pk_fma_f32 v[38:39], v[38:39], v[234:235], v[110:111]
	v_pk_fma_f32 v[36:37], v[36:37], v[232:233], v[108:109]
	v_cvt_pk_bf16_f32 v36, v36, v37
	v_cvt_pk_bf16_f32 v37, v38, v39
	global_store_dwordx2 v[60:61], v[36:37], off offset:1024
	v_cndmask_b32_e64 v88, v186, v67, s[2:3]
	v_ashrrev_i32_e32 v89, 31, v88
	v_lshl_add_u64 v[88:89], v[88:89], 2, s[18:19]
	v_lshl_add_u64 v[90:91], v[88:89], 0, s[14:15]
	v_lshl_add_u64 v[92:93], v[90:91], 0, v[128:129]
	v_mov_b32_e32 v50, v29
	v_mov_b32_e32 v51, v25
	v_mov_b32_e32 v48, v28
	v_mov_b32_e32 v49, v24
	v_pk_mul_f32 v[50:51], v[50:51], v[50:51]
	v_mov_b32_e32 v86, v23
	v_pk_fma_f32 v[48:49], v[48:49], v[48:49], v[50:51]
	v_mov_b32_e32 v87, v7
	v_pk_fma_f32 v[48:49], v[52:53], v[52:53], v[48:49]
	v_mov_b32_e32 v52, v17
	v_pk_fma_f32 v[48:49], v[54:55], v[54:55], v[48:49]
	v_mov_b32_e32 v53, v13
	v_add_f32_e32 v48, v48, v49
	v_mov_b32_e32 v50, v16
	v_mov_b32_e32 v51, v12
	v_pk_mul_f32 v[52:53], v[52:53], v[52:53]
	v_mov_b32_e32 v54, v18
	v_mov_b32_e32 v55, v14
	v_pk_fma_f32 v[50:51], v[50:51], v[50:51], v[52:53]
	v_pk_mul_f32 v[32:33], v[32:33], v[220:221]
	v_pk_mul_f32 v[34:35], v[34:35], v[222:223]
	v_pk_fma_f32 v[34:35], v[34:35], v[238:239], v[74:75]
	v_pk_fma_f32 v[32:33], v[32:33], v[236:237], v[72:73]
	v_lshl_add_u64 v[44:45], v[88:89], 0, s[16:17]
	v_cvt_pk_bf16_f32 v32, v32, v33
	v_cvt_pk_bf16_f32 v33, v34, v35
	global_store_dwordx2 v[60:61], v[32:33], off offset:1536
	v_lshl_add_u64 v[40:41], v[44:45], 0, v[128:129]
	v_pk_mul_f32 v[46:47], v[58:59], v[58:59]
	v_pk_fma_f32 v[46:47], v[56:57], v[56:57], v[46:47]
	v_mov_b32_e32 v60, v9
	v_pk_fma_f32 v[46:47], v[82:83], v[82:83], v[46:47]
	v_mov_b32_e32 v61, v1
	v_pk_fma_f32 v[46:47], v[86:87], v[86:87], v[46:47]
	v_mov_b32_e32 v58, v8
	v_add_f32_e32 v46, v48, v46
	v_add_f32_e32 v46, v46, v47
	v_mov_b32_e32 v59, v0
	v_pk_mul_f32 v[60:61], v[60:61], v[60:61]
	v_add_f32_dpp v46, v46, v46 quad_perm:[1,0,3,2] row_mask:0xf bank_mask:0xf bound_ctrl:1
	v_mov_b32_e32 v56, v19
	v_mov_b32_e32 v57, v15
	v_add_f32_dpp v46, v46, v46 quad_perm:[2,3,0,1] row_mask:0xf bank_mask:0xf bound_ctrl:1
	v_pk_fma_f32 v[52:53], v[58:59], v[58:59], v[60:61]
	v_pk_fma_f32 v[50:51], v[54:55], v[54:55], v[50:51]
	v_add_f32_dpp v46, v46, v46 row_half_mirror row_mask:0xf bank_mask:0xf bound_ctrl:1
	v_mov_b32_e32 v82, v11
	v_mov_b32_e32 v83, v3
	v_add_f32_dpp v46, v46, v46 row_mirror row_mask:0xf bank_mask:0xf bound_ctrl:1
	v_pk_fma_f32 v[52:53], v[62:63], v[62:63], v[52:53]
	v_readlane_b32 s4, v46, 16
	v_readlane_b32 s5, v46, 48
	v_readlane_b32 s2, v46, 0
	v_readlane_b32 s3, v46, 32
	v_mov_b32_e32 v46, s4
	v_mov_b32_e32 v47, s5
	v_pk_add_f32 v[46:47], s[2:3], v[46:47]
	v_pk_fma_f32 v[50:51], v[56:57], v[56:57], v[50:51]
	v_mov_b32_e32 v49, v46
	v_pk_fma_f32 v[52:53], v[82:83], v[82:83], v[52:53]
	v_add_f32_e32 v46, v50, v51
	v_add_f32_e32 v46, v46, v52
	v_add_f32_e32 v46, v46, v53
	s_nop 1
	v_add_f32_dpp v46, v46, v46 quad_perm:[1,0,3,2] row_mask:0xf bank_mask:0xf bound_ctrl:1
	s_nop 0
	s_nop 0
	v_add_f32_dpp v46, v46, v46 quad_perm:[2,3,0,1] row_mask:0xf bank_mask:0xf bound_ctrl:1
	s_nop 1
	v_add_f32_dpp v46, v46, v46 row_half_mirror row_mask:0xf bank_mask:0xf bound_ctrl:1
	s_nop 1
	v_add_f32_dpp v46, v46, v46 row_mirror row_mask:0xf bank_mask:0xf bound_ctrl:1
	s_nop 0
	v_readlane_b32 s4, v46, 16
	v_readlane_b32 s5, v46, 48
	v_readlane_b32 s2, v46, 0
	v_readlane_b32 s3, v46, 32
	v_mov_b32_e32 v50, s4
	v_mov_b32_e32 v51, s5
	v_pk_add_f32 v[50:51], s[2:3], v[50:51]
	s_nop 0
	v_mov_b32_e32 v48, v50
	v_mov_b32_e32 v46, v51
	v_pk_add_f32 v[46:47], v[48:49], v[46:47]
	s_nop 0
	v_pk_fma_f32 v[46:47], v[46:47], s[12:13], v[84:85] op_sel_hi:[1,0,0]
	s_nop 0
	v_mul_f32_e32 v48, 0x4b800000, v47
	v_cmp_gt_f32_e64 s[2:3], s8, v47
	s_nop 1
	v_cndmask_b32_e64 v47, v47, v48, s[2:3]
	v_rsq_f32_e32 v47, v47
	v_lshlrev_b64 v[48:49], 11, v[80:81]
	v_lshl_add_u64 v[48:49], v[70:71], 0, v[48:49]
	v_mul_f32_e32 v50, 0x45800000, v47
	v_cndmask_b32_e64 v50, v47, v50, s[2:3]
	v_pk_mul_f32 v[30:31], v[30:31], v[50:51] op_sel_hi:[1,0]
	v_pk_mul_f32 v[28:29], v[28:29], v[50:51] op_sel_hi:[1,0]
	v_pk_mul_f32 v[30:31], v[30:31], v[210:211]
	v_pk_mul_f32 v[28:29], v[28:29], v[208:209]
	v_pk_fma_f32 v[30:31], v[30:31], v[226:227], v[242:243]
	v_pk_fma_f32 v[28:29], v[28:29], v[224:225], v[240:241]
	v_cvt_pk_bf16_f32 v28, v28, v29
	v_cvt_pk_bf16_f32 v29, v30, v31
	global_store_dwordx2 v[48:49], v[28:29], off
	v_pk_mul_f32 v[26:27], v[26:27], v[50:51] op_sel_hi:[1,0]
	v_pk_mul_f32 v[24:25], v[24:25], v[50:51] op_sel_hi:[1,0]
	v_pk_mul_f32 v[22:23], v[22:23], v[50:51] op_sel_hi:[1,0]
	v_pk_mul_f32 v[20:21], v[20:21], v[50:51] op_sel_hi:[1,0]
	v_pk_mul_f32 v[6:7], v[6:7], v[50:51] op_sel_hi:[1,0]
	v_pk_mul_f32 v[4:5], v[4:5], v[50:51] op_sel_hi:[1,0]
	v_readlane_b32 s2, v252, 26
	v_pk_mul_f32 v[24:25], v[24:25], v[212:213]
	v_pk_mul_f32 v[26:27], v[26:27], v[214:215]
	v_pk_fma_f32 v[26:27], v[26:27], v[230:231], v[246:247]
	v_pk_fma_f32 v[24:25], v[24:25], v[228:229], v[244:245]
	v_cvt_pk_bf16_f32 v24, v24, v25
	v_cvt_pk_bf16_f32 v25, v26, v27
	global_store_dwordx2 v[48:49], v[24:25], off offset:512
	v_pk_mul_f32 v[20:21], v[20:21], v[216:217]
	v_pk_mul_f32 v[22:23], v[22:23], v[218:219]
	v_pk_fma_f32 v[22:23], v[22:23], v[234:235], v[110:111]
	v_pk_fma_f32 v[20:21], v[20:21], v[232:233], v[108:109]
	v_cvt_pk_bf16_f32 v20, v20, v21
	v_cvt_pk_bf16_f32 v21, v22, v23
	global_store_dwordx2 v[48:49], v[20:21], off offset:1024
	v_cndmask_b32_e32 v32, v186, v67, vcc
	v_ashrrev_i32_e32 v33, 31, v32
	v_lshl_add_u64 v[32:33], v[32:33], 2, s[18:19]
	v_lshl_add_u64 v[34:35], v[32:33], 0, s[14:15]
	v_lshl_add_u64 v[32:33], v[32:33], 0, s[16:17]
	v_cmp_gt_f32_e32 vcc, s8, v46
	v_pk_mul_f32 v[4:5], v[4:5], v[220:221]
	v_pk_mul_f32 v[6:7], v[6:7], v[222:223]
	v_pk_fma_f32 v[6:7], v[6:7], v[238:239], v[74:75]
	v_pk_fma_f32 v[4:5], v[4:5], v[236:237], v[72:73]
	v_lshl_add_u64 v[20:21], v[34:35], 0, v[128:129]
	v_cvt_pk_bf16_f32 v4, v4, v5
	v_cvt_pk_bf16_f32 v5, v6, v7
	global_store_dwordx2 v[48:49], v[4:5], off offset:1536
	v_lshl_add_u64 v[24:25], v[32:33], 0, v[128:129]
	v_mul_f32_e32 v28, 0x4b800000, v46
	v_cndmask_b32_e32 v28, v46, v28, vcc
	v_rsq_f32_e32 v30, v28
	v_lshlrev_b64 v[28:29], 11, v[78:79]
	v_lshl_add_u64 v[28:29], v[70:71], 0, v[28:29]
	v_mul_f32_e32 v31, 0x45800000, v30
	v_cndmask_b32_e32 v30, v30, v31, vcc
	v_pk_mul_f32 v[18:19], v[18:19], v[30:31] op_sel_hi:[1,0]
	v_pk_mul_f32 v[16:17], v[16:17], v[30:31] op_sel_hi:[1,0]
	v_pk_mul_f32 v[14:15], v[14:15], v[30:31] op_sel_hi:[1,0]
	v_pk_mul_f32 v[12:13], v[12:13], v[30:31] op_sel_hi:[1,0]
	v_pk_mul_f32 v[10:11], v[10:11], v[30:31] op_sel_hi:[1,0]
	v_pk_mul_f32 v[8:9], v[8:9], v[30:31] op_sel_hi:[1,0]
	v_pk_mul_f32 v[2:3], v[2:3], v[30:31] op_sel_hi:[1,0]
	v_pk_mul_f32 v[0:1], v[0:1], v[30:31] op_sel_hi:[1,0]
	v_pk_mul_f32 v[4:5], v[16:17], v[208:209]
	v_pk_mul_f32 v[6:7], v[18:19], v[210:211]
	v_pk_fma_f32 v[6:7], v[6:7], v[226:227], v[242:243]
	v_pk_fma_f32 v[4:5], v[4:5], v[224:225], v[240:241]
	v_cvt_pk_bf16_f32 v4, v4, v5
	v_cvt_pk_bf16_f32 v5, v6, v7
	global_store_dwordx2 v[28:29], v[4:5], off
	v_pk_mul_f32 v[4:5], v[12:13], v[212:213]
	v_pk_mul_f32 v[6:7], v[14:15], v[214:215]
	v_pk_fma_f32 v[6:7], v[6:7], v[230:231], v[246:247]
	v_pk_fma_f32 v[4:5], v[4:5], v[228:229], v[244:245]
	v_cvt_pk_bf16_f32 v4, v4, v5
	v_cvt_pk_bf16_f32 v5, v6, v7
	global_store_dwordx2 v[28:29], v[4:5], off offset:512
	v_pk_mul_f32 v[4:5], v[8:9], v[216:217]
	v_pk_mul_f32 v[6:7], v[10:11], v[218:219]
	v_pk_fma_f32 v[6:7], v[6:7], v[234:235], v[110:111]
	v_pk_fma_f32 v[4:5], v[4:5], v[232:233], v[108:109]
	v_cvt_pk_bf16_f32 v4, v4, v5
	v_cvt_pk_bf16_f32 v5, v6, v7
	global_store_dwordx2 v[28:29], v[4:5], off offset:1024
	v_pk_mul_f32 v[0:1], v[0:1], v[220:221]
	v_pk_mul_f32 v[2:3], v[2:3], v[222:223]
	v_pk_fma_f32 v[2:3], v[2:3], v[238:239], v[74:75]
	v_pk_fma_f32 v[0:1], v[0:1], v[236:237], v[72:73]
	s_nop 0
	v_cvt_pk_bf16_f32 v0, v0, v1
	v_cvt_pk_bf16_f32 v1, v2, v3
	global_store_dwordx2 v[28:29], v[0:1], off offset:1536
	s_nop 0
	v_lshl_add_u32 v64, s2, 4, v64
	s_mov_b32 s2, 0x87ff
	v_cmp_lt_i32_e32 vcc, s2, v64
	s_or_b64 s[10:11], vcc, s[10:11]
	s_andn2_b64 exec, exec, s[10:11]
	s_cbranch_execz .LBB0_881

.LBB0_1902:
	s_or_b64 exec, exec, s[10:11]
	v_ashrrev_i32_e32 v67, 12, v64
	v_mul_i32_i24_e32 v67, 0x2400, v67
	v_cndmask_b32_e64 v86, v186, v67, s[8:9]
	v_readlane_b32 s16, v254, 27
	s_waitcnt vmcnt(11)
	v_mov_b32_e32 v92, v61
	s_waitcnt vmcnt(10)
	v_mov_b32_e32 v93, v57
	v_mov_b32_e32 v84, v60
	v_mov_b32_e32 v85, v56
	v_ashrrev_i32_e32 v87, 31, v86
	v_readlane_b32 s17, v254, 28
	v_pk_mul_f32 v[92:93], v[92:93], v[92:93]
	s_waitcnt vmcnt(9)
	v_mov_b32_e32 v94, v53
	v_lshl_add_u64 v[90:91], v[86:87], 2, s[16:17]
	v_pk_fma_f32 v[84:85], v[84:85], v[84:85], v[92:93]
	v_mov_b32_e32 v92, v62
	v_mov_b32_e32 v93, v58
	v_lshl_add_u64 v[98:99], v[90:91], 0, s[18:19]
	v_pk_fma_f32 v[84:85], v[92:93], v[92:93], v[84:85]
	v_mov_b32_e32 v92, v63
	v_mov_b32_e32 v93, v59
	s_waitcnt vmcnt(8)
	v_mov_b32_e32 v95, v49
	s_mov_b64 s[14:15], 0x6000
	v_lshl_add_u64 v[0:1], v[0:1], 0, v[128:129]
	v_lshl_add_u64 v[86:87], v[98:99], 0, v[128:129]
	v_pk_fma_f32 v[84:85], v[92:93], v[92:93], v[84:85]
	v_mov_b32_e32 v92, v52
	v_mov_b32_e32 v93, v48
	v_pk_mul_f32 v[94:95], v[94:95], v[94:95]
	v_lshl_add_u64 v[102:103], v[90:91], 0, s[14:15]
	global_load_dwordx4 v[16:19], v[0:1], off
	global_load_dwordx4 v[12:15], v[0:1], off offset:1024
	global_load_dwordx4 v[8:11], v[0:1], off offset:2048
	s_nop 0
	global_load_dwordx4 v[0:3], v[0:1], off offset:3072
	v_pk_fma_f32 v[100:101], v[92:93], v[92:93], v[94:95]
	v_lshl_add_u64 v[94:95], v[102:103], 0, v[128:129]
	v_mov_b32_e32 v104, v54
	global_load_dwordx4 v[208:211], v[68:69], off
	global_load_dwordx4 v[224:227], v[86:87], off
	global_load_dwordx4 v[240:243], v[94:95], off
	global_load_dwordx4 v[212:215], v[68:69], off offset:1024
	global_load_dwordx4 v[228:231], v[86:87], off offset:1024
	global_load_dwordx4 v[244:247], v[94:95], off offset:1024
	global_load_dwordx4 v[216:219], v[68:69], off offset:2048
	global_load_dwordx4 v[232:235], v[86:87], off offset:2048
	global_load_dwordx4 v[108:111], v[94:95], off offset:2048
	global_load_dwordx4 v[220:223], v[68:69], off offset:3072
	global_load_dwordx4 v[236:239], v[86:87], off offset:3072
	global_load_dwordx4 v[72:75], v[94:95], off offset:3072
	v_mov_b32_e32 v105, v50
	v_pk_fma_f32 v[100:101], v[104:105], v[104:105], v[100:101]
	v_mov_b32_e32 v104, v55
	v_mov_b32_e32 v105, v51
	v_pk_fma_f32 v[100:101], v[104:105], v[104:105], v[100:101]
	v_add_f32_e32 v112, v84, v85
	v_add_f32_e32 v112, v112, v100
	s_waitcnt vmcnt(23)
	v_mov_b32_e32 v104, v45
	s_waitcnt vmcnt(22)
	v_mov_b32_e32 v105, v41
	v_add_f32_e32 v112, v112, v101
	v_mov_b32_e32 v100, v44
	v_mov_b32_e32 v101, v40
	v_pk_mul_f32 v[104:105], v[104:105], v[104:105]
	v_add_f32_dpp v112, v112, v112 quad_perm:[1,0,3,2] row_mask:0xf bank_mask:0xf bound_ctrl:1
	v_pk_fma_f32 v[100:101], v[100:101], v[100:101], v[104:105]
	v_mov_b32_e32 v104, v46
	v_mov_b32_e32 v105, v42
	v_pk_fma_f32 v[100:101], v[104:105], v[104:105], v[100:101]
	v_mov_b32_e32 v104, v47
	v_mov_b32_e32 v105, v43
	s_waitcnt vmcnt(21)
	v_mov_b32_e32 v106, v37
	s_waitcnt vmcnt(20)
	v_mov_b32_e32 v107, v33
	v_add_f32_dpp v112, v112, v112 quad_perm:[2,3,0,1] row_mask:0xf bank_mask:0xf bound_ctrl:1
	v_pk_fma_f32 v[100:101], v[104:105], v[104:105], v[100:101]
	v_mov_b32_e32 v104, v36
	v_mov_b32_e32 v105, v32
	v_pk_mul_f32 v[106:107], v[106:107], v[106:107]
	v_add_f32_dpp v112, v112, v112 row_half_mirror row_mask:0xf bank_mask:0xf bound_ctrl:1
	v_pk_fma_f32 v[104:105], v[104:105], v[104:105], v[106:107]
	v_mov_b32_e32 v106, v38
	v_mov_b32_e32 v107, v34
	v_add_f32_dpp v112, v112, v112 row_mirror row_mask:0xf bank_mask:0xf bound_ctrl:1
	v_pk_fma_f32 v[104:105], v[106:107], v[106:107], v[104:105]
	v_mov_b32_e32 v106, v39
	v_mov_b32_e32 v107, v35
	v_readlane_b32 s8, v112, 0
	v_readlane_b32 s10, v112, 16
	v_readlane_b32 s9, v112, 32
	v_readlane_b32 s11, v112, 48
	v_pk_fma_f32 v[104:105], v[106:107], v[106:107], v[104:105]
	v_add_f32_e32 v112, v100, v101
	v_add_f32_e32 v112, v112, v104
	v_add_f32_e32 v112, v112, v105
	v_mov_b32_e32 v84, s10
	v_mov_b32_e32 v85, s11
	v_add_f32_dpp v112, v112, v112 quad_perm:[1,0,3,2] row_mask:0xf bank_mask:0xf bound_ctrl:1
	v_pk_add_f32 v[84:85], s[8:9], v[84:85]
	v_lshlrev_b64 v[104:105], 11, v[64:65]
	v_add_f32_dpp v112, v112, v112 quad_perm:[2,3,0,1] row_mask:0xf bank_mask:0xf bound_ctrl:1
	v_mov_b32_e32 v107, v84
	v_lshl_add_u64 v[104:105], v[70:71], 0, v[104:105]
	v_add_f32_dpp v112, v112, v112 row_half_mirror row_mask:0xf bank_mask:0xf bound_ctrl:1
	s_waitcnt vmcnt(11)
	s_waitcnt vmcnt(0)
	v_pk_add_f32 v[226:227], v[226:227], 1.0 op_sel_hi:[1,0]
	v_pk_add_f32 v[224:225], v[224:225], 1.0 op_sel_hi:[1,0]
	v_pk_add_f32 v[230:231], v[230:231], 1.0 op_sel_hi:[1,0]
	v_pk_add_f32 v[228:229], v[228:229], 1.0 op_sel_hi:[1,0]
	v_pk_add_f32 v[234:235], v[234:235], 1.0 op_sel_hi:[1,0]
	v_pk_add_f32 v[232:233], v[232:233], 1.0 op_sel_hi:[1,0]
	v_pk_add_f32 v[238:239], v[238:239], 1.0 op_sel_hi:[1,0]
	v_pk_add_f32 v[236:237], v[236:237], 1.0 op_sel_hi:[1,0]
	v_add_f32_dpp v112, v112, v112 row_mirror row_mask:0xf bank_mask:0xf bound_ctrl:1
	s_nop 0
	v_readlane_b32 s10, v112, 16
	v_readlane_b32 s11, v112, 48
	v_readlane_b32 s8, v112, 0
	v_readlane_b32 s9, v112, 32
	v_mov_b32_e32 v100, s10
	v_mov_b32_e32 v101, s11
	v_pk_add_f32 v[100:101], s[8:9], v[100:101]
	s_mov_b32 s10, 0x3a800000
	v_mov_b32_e32 v106, v100
	v_mov_b32_e32 v84, v101
	v_pk_add_f32 v[100:101], v[106:107], v[84:85]
	v_mov_b64_e32 v[84:85], s[38:39]
	v_pk_fma_f32 v[100:101], v[100:101], s[10:11], v[84:85] op_sel_hi:[1,0,0]
	v_mul_f32_e32 v65, 0x4b800000, v101
	v_cmp_gt_f32_e64 s[8:9], s20, v101
	s_nop 1
	v_cndmask_b32_e64 v65, v101, v65, s[8:9]
	v_rsq_f32_e32 v65, v65
	s_nop 0
	v_mul_f32_e32 v188, 0x45800000, v65
	v_cndmask_b32_e64 v106, v65, v188, s[8:9]
	v_pk_mul_f32 v[62:63], v[62:63], v[106:107] op_sel_hi:[1,0]
	v_pk_mul_f32 v[60:61], v[60:61], v[106:107] op_sel_hi:[1,0]
	v_pk_mul_f32 v[62:63], v[62:63], v[210:211]
	v_pk_mul_f32 v[60:61], v[60:61], v[208:209]
	v_pk_fma_f32 v[62:63], v[62:63], v[226:227], v[242:243]
	v_pk_fma_f32 v[60:61], v[60:61], v[224:225], v[240:241]
	v_cvt_pk_bf16_f32 v60, v60, v61
	v_cvt_pk_bf16_f32 v61, v62, v63
	global_store_dwordx2 v[104:105], v[60:61], off
	v_pk_mul_f32 v[58:59], v[58:59], v[106:107] op_sel_hi:[1,0]
	v_pk_mul_f32 v[56:57], v[56:57], v[106:107] op_sel_hi:[1,0]
	v_pk_mul_f32 v[54:55], v[54:55], v[106:107] op_sel_hi:[1,0]
	v_pk_mul_f32 v[52:53], v[52:53], v[106:107] op_sel_hi:[1,0]
	v_pk_mul_f32 v[50:51], v[50:51], v[106:107] op_sel_hi:[1,0]
	v_pk_mul_f32 v[48:49], v[48:49], v[106:107] op_sel_hi:[1,0]
	v_pk_mul_f32 v[56:57], v[56:57], v[212:213]
	v_pk_mul_f32 v[58:59], v[58:59], v[214:215]
	v_pk_fma_f32 v[58:59], v[58:59], v[230:231], v[246:247]
	v_pk_fma_f32 v[56:57], v[56:57], v[228:229], v[244:245]
	v_cvt_pk_bf16_f32 v56, v56, v57
	v_cvt_pk_bf16_f32 v57, v58, v59
	global_store_dwordx2 v[104:105], v[56:57], off offset:512
	v_pk_mul_f32 v[52:53], v[52:53], v[216:217]
	v_pk_mul_f32 v[54:55], v[54:55], v[218:219]
	v_pk_fma_f32 v[54:55], v[54:55], v[234:235], v[110:111]
	v_pk_fma_f32 v[52:53], v[52:53], v[232:233], v[108:109]
	v_cvt_pk_bf16_f32 v52, v52, v53
	v_cvt_pk_bf16_f32 v53, v54, v55
	global_store_dwordx2 v[104:105], v[52:53], off offset:1024
	v_cndmask_b32_e64 v86, v186, v67, s[6:7]
	v_ashrrev_i32_e32 v87, 31, v86
	v_lshl_add_u64 v[86:87], v[86:87], 2, s[16:17]
	v_lshl_add_u64 v[88:89], v[86:87], 0, s[18:19]
	v_lshl_add_u64 v[86:87], v[86:87], 0, s[14:15]
	v_cmp_gt_f32_e64 s[6:7], s20, v100
	v_pk_mul_f32 v[48:49], v[48:49], v[220:221]
	v_pk_mul_f32 v[50:51], v[50:51], v[222:223]
	v_pk_fma_f32 v[50:51], v[50:51], v[238:239], v[74:75]
	v_pk_fma_f32 v[48:49], v[48:49], v[236:237], v[72:73]
	v_lshl_add_u64 v[52:53], v[88:89], 0, v[128:129]
	v_cvt_pk_bf16_f32 v48, v48, v49
	v_cvt_pk_bf16_f32 v49, v50, v51
	global_store_dwordx2 v[104:105], v[48:49], off offset:1536
	v_lshl_add_u64 v[56:57], v[86:87], 0, v[128:129]
	v_mul_f32_e32 v60, 0x4b800000, v100
	v_cndmask_b32_e64 v60, v100, v60, s[6:7]
	v_rsq_f32_e32 v62, v60
	v_lshlrev_b64 v[60:61], 11, v[82:83]
	v_lshl_add_u64 v[60:61], v[70:71], 0, v[60:61]
	v_mov_b32_e32 v82, v22
	v_mul_f32_e32 v63, 0x45800000, v62
	v_cndmask_b32_e64 v62, v62, v63, s[6:7]
	v_pk_mul_f32 v[46:47], v[46:47], v[62:63] op_sel_hi:[1,0]
	v_pk_mul_f32 v[44:45], v[44:45], v[62:63] op_sel_hi:[1,0]
	v_pk_mul_f32 v[42:43], v[42:43], v[62:63] op_sel_hi:[1,0]
	v_pk_mul_f32 v[40:41], v[40:41], v[62:63] op_sel_hi:[1,0]
	v_pk_mul_f32 v[38:39], v[38:39], v[62:63] op_sel_hi:[1,0]
	v_pk_mul_f32 v[36:37], v[36:37], v[62:63] op_sel_hi:[1,0]
	v_pk_mul_f32 v[34:35], v[34:35], v[62:63] op_sel_hi:[1,0]
	v_pk_mul_f32 v[32:33], v[32:33], v[62:63] op_sel_hi:[1,0]
	v_mov_b32_e32 v83, v6
	v_mov_b32_e32 v62, v10
	v_mov_b32_e32 v63, v2
	v_pk_mul_f32 v[44:45], v[44:45], v[208:209]
	v_pk_mul_f32 v[46:47], v[46:47], v[210:211]
	v_pk_fma_f32 v[46:47], v[46:47], v[226:227], v[242:243]
	v_pk_fma_f32 v[44:45], v[44:45], v[224:225], v[240:241]
	v_cvt_pk_bf16_f32 v44, v44, v45
	v_cvt_pk_bf16_f32 v45, v46, v47
	global_store_dwordx2 v[60:61], v[44:45], off
	v_mov_b32_e32 v58, v21
	v_mov_b32_e32 v59, v5
	v_mov_b32_e32 v56, v20
	v_mov_b32_e32 v57, v4
	v_pk_mul_f32 v[40:41], v[40:41], v[212:213]
	v_pk_mul_f32 v[42:43], v[42:43], v[214:215]
	v_pk_fma_f32 v[42:43], v[42:43], v[230:231], v[246:247]
	v_pk_fma_f32 v[40:41], v[40:41], v[228:229], v[244:245]
	v_cvt_pk_bf16_f32 v40, v40, v41
	v_cvt_pk_bf16_f32 v41, v42, v43
	global_store_dwordx2 v[60:61], v[40:41], off offset:512
	v_mov_b32_e32 v52, v30
	v_mov_b32_e32 v53, v26
	v_mov_b32_e32 v54, v31
	v_mov_b32_e32 v55, v27
	v_pk_mul_f32 v[36:37], v[36:37], v[216:217]
	v_pk_mul_f32 v[38:39], v[38:39], v[218:219]
	v_pk_fma_f32 v[38:39], v[38:39], v[234:235], v[110:111]
	v_pk_fma_f32 v[36:37], v[36:37], v[232:233], v[108:109]
	v_cvt_pk_bf16_f32 v36, v36, v37
	v_cvt_pk_bf16_f32 v37, v38, v39
	global_store_dwordx2 v[60:61], v[36:37], off offset:1024
	v_cndmask_b32_e64 v88, v186, v67, s[4:5]
	v_ashrrev_i32_e32 v89, 31, v88
	v_lshl_add_u64 v[88:89], v[88:89], 2, s[16:17]
	v_lshl_add_u64 v[90:91], v[88:89], 0, s[18:19]
	v_lshl_add_u64 v[92:93], v[90:91], 0, v[128:129]
	v_mov_b32_e32 v50, v29
	v_mov_b32_e32 v51, v25
	v_mov_b32_e32 v48, v28
	v_mov_b32_e32 v49, v24
	v_pk_mul_f32 v[50:51], v[50:51], v[50:51]
	v_mov_b32_e32 v86, v23
	v_pk_fma_f32 v[48:49], v[48:49], v[48:49], v[50:51]
	v_mov_b32_e32 v87, v7
	v_pk_fma_f32 v[48:49], v[52:53], v[52:53], v[48:49]
	v_mov_b32_e32 v52, v17
	v_pk_fma_f32 v[48:49], v[54:55], v[54:55], v[48:49]
	v_mov_b32_e32 v53, v13
	v_add_f32_e32 v48, v48, v49
	v_mov_b32_e32 v50, v16
	v_mov_b32_e32 v51, v12
	v_pk_mul_f32 v[52:53], v[52:53], v[52:53]
	v_mov_b32_e32 v54, v18
	v_mov_b32_e32 v55, v14
	v_pk_fma_f32 v[50:51], v[50:51], v[50:51], v[52:53]
	v_pk_mul_f32 v[32:33], v[32:33], v[220:221]
	v_pk_mul_f32 v[34:35], v[34:35], v[222:223]
	v_pk_fma_f32 v[34:35], v[34:35], v[238:239], v[74:75]
	v_pk_fma_f32 v[32:33], v[32:33], v[236:237], v[72:73]
	v_lshl_add_u64 v[44:45], v[88:89], 0, s[14:15]
	v_cvt_pk_bf16_f32 v32, v32, v33
	v_cvt_pk_bf16_f32 v33, v34, v35
	global_store_dwordx2 v[60:61], v[32:33], off offset:1536
	v_lshl_add_u64 v[40:41], v[44:45], 0, v[128:129]
	v_pk_mul_f32 v[46:47], v[58:59], v[58:59]
	v_pk_fma_f32 v[46:47], v[56:57], v[56:57], v[46:47]
	v_mov_b32_e32 v60, v9
	v_pk_fma_f32 v[46:47], v[82:83], v[82:83], v[46:47]
	v_mov_b32_e32 v61, v1
	v_pk_fma_f32 v[46:47], v[86:87], v[86:87], v[46:47]
	v_mov_b32_e32 v58, v8
	v_add_f32_e32 v46, v48, v46
	v_add_f32_e32 v46, v46, v47
	v_mov_b32_e32 v59, v0
	v_pk_mul_f32 v[60:61], v[60:61], v[60:61]
	v_add_f32_dpp v46, v46, v46 quad_perm:[1,0,3,2] row_mask:0xf bank_mask:0xf bound_ctrl:1
	v_mov_b32_e32 v56, v19
	v_mov_b32_e32 v57, v15
	v_add_f32_dpp v46, v46, v46 quad_perm:[2,3,0,1] row_mask:0xf bank_mask:0xf bound_ctrl:1
	v_pk_fma_f32 v[52:53], v[58:59], v[58:59], v[60:61]
	v_pk_fma_f32 v[50:51], v[54:55], v[54:55], v[50:51]
	v_add_f32_dpp v46, v46, v46 row_half_mirror row_mask:0xf bank_mask:0xf bound_ctrl:1
	v_mov_b32_e32 v82, v11
	v_mov_b32_e32 v83, v3
	v_add_f32_dpp v46, v46, v46 row_mirror row_mask:0xf bank_mask:0xf bound_ctrl:1
	v_pk_fma_f32 v[52:53], v[62:63], v[62:63], v[52:53]
	v_readlane_b32 s6, v46, 16
	v_readlane_b32 s7, v46, 48
	v_readlane_b32 s4, v46, 0
	v_readlane_b32 s5, v46, 32
	v_mov_b32_e32 v46, s6
	v_mov_b32_e32 v47, s7
	v_pk_add_f32 v[46:47], s[4:5], v[46:47]
	v_pk_fma_f32 v[50:51], v[56:57], v[56:57], v[50:51]
	v_mov_b32_e32 v49, v46
	v_pk_fma_f32 v[52:53], v[82:83], v[82:83], v[52:53]
	v_add_f32_e32 v46, v50, v51
	v_add_f32_e32 v46, v46, v52
	v_add_f32_e32 v46, v46, v53
	s_nop 1
	v_add_f32_dpp v46, v46, v46 quad_perm:[1,0,3,2] row_mask:0xf bank_mask:0xf bound_ctrl:1
	s_nop 0
	s_nop 0
	v_add_f32_dpp v46, v46, v46 quad_perm:[2,3,0,1] row_mask:0xf bank_mask:0xf bound_ctrl:1
	s_nop 1
	v_add_f32_dpp v46, v46, v46 row_half_mirror row_mask:0xf bank_mask:0xf bound_ctrl:1
	s_nop 1
	v_add_f32_dpp v46, v46, v46 row_mirror row_mask:0xf bank_mask:0xf bound_ctrl:1
	s_nop 0
	v_readlane_b32 s6, v46, 16
	v_readlane_b32 s7, v46, 48
	v_readlane_b32 s4, v46, 0
	v_readlane_b32 s5, v46, 32
	v_mov_b32_e32 v50, s6
	v_mov_b32_e32 v51, s7
	v_pk_add_f32 v[50:51], s[4:5], v[50:51]
	s_nop 0
	v_mov_b32_e32 v48, v50
	v_mov_b32_e32 v46, v51
	v_pk_add_f32 v[46:47], v[48:49], v[46:47]
	s_nop 0
	v_pk_fma_f32 v[46:47], v[46:47], s[10:11], v[84:85] op_sel_hi:[1,0,0]
	s_nop 0
	v_mul_f32_e32 v48, 0x4b800000, v47
	v_cmp_gt_f32_e64 s[4:5], s20, v47
	s_nop 1
	v_cndmask_b32_e64 v47, v47, v48, s[4:5]
	v_rsq_f32_e32 v47, v47
	v_lshlrev_b64 v[48:49], 11, v[80:81]
	v_lshl_add_u64 v[48:49], v[70:71], 0, v[48:49]
	v_mul_f32_e32 v50, 0x45800000, v47
	v_cndmask_b32_e64 v50, v47, v50, s[4:5]
	v_pk_mul_f32 v[30:31], v[30:31], v[50:51] op_sel_hi:[1,0]
	v_pk_mul_f32 v[28:29], v[28:29], v[50:51] op_sel_hi:[1,0]
	v_pk_mul_f32 v[30:31], v[30:31], v[210:211]
	v_pk_mul_f32 v[28:29], v[28:29], v[208:209]
	v_pk_fma_f32 v[30:31], v[30:31], v[226:227], v[242:243]
	v_pk_fma_f32 v[28:29], v[28:29], v[224:225], v[240:241]
	v_cvt_pk_bf16_f32 v28, v28, v29
	v_cvt_pk_bf16_f32 v29, v30, v31
	global_store_dwordx2 v[48:49], v[28:29], off
	v_pk_mul_f32 v[26:27], v[26:27], v[50:51] op_sel_hi:[1,0]
	v_pk_mul_f32 v[24:25], v[24:25], v[50:51] op_sel_hi:[1,0]
	v_pk_mul_f32 v[22:23], v[22:23], v[50:51] op_sel_hi:[1,0]
	v_pk_mul_f32 v[20:21], v[20:21], v[50:51] op_sel_hi:[1,0]
	v_pk_mul_f32 v[6:7], v[6:7], v[50:51] op_sel_hi:[1,0]
	v_pk_mul_f32 v[4:5], v[4:5], v[50:51] op_sel_hi:[1,0]
	v_readlane_b32 s4, v252, 26
	v_pk_mul_f32 v[24:25], v[24:25], v[212:213]
	v_pk_mul_f32 v[26:27], v[26:27], v[214:215]
	v_pk_fma_f32 v[26:27], v[26:27], v[230:231], v[246:247]
	v_pk_fma_f32 v[24:25], v[24:25], v[228:229], v[244:245]
	v_cvt_pk_bf16_f32 v24, v24, v25
	v_cvt_pk_bf16_f32 v25, v26, v27
	global_store_dwordx2 v[48:49], v[24:25], off offset:512
	v_pk_mul_f32 v[20:21], v[20:21], v[216:217]
	v_pk_mul_f32 v[22:23], v[22:23], v[218:219]
	v_pk_fma_f32 v[22:23], v[22:23], v[234:235], v[110:111]
	v_pk_fma_f32 v[20:21], v[20:21], v[232:233], v[108:109]
	v_cvt_pk_bf16_f32 v20, v20, v21
	v_cvt_pk_bf16_f32 v21, v22, v23
	global_store_dwordx2 v[48:49], v[20:21], off offset:1024
	v_cndmask_b32_e32 v32, v186, v67, vcc
	v_ashrrev_i32_e32 v33, 31, v32
	v_lshl_add_u64 v[32:33], v[32:33], 2, s[16:17]
	v_lshl_add_u64 v[34:35], v[32:33], 0, s[18:19]
	v_lshl_add_u64 v[32:33], v[32:33], 0, s[14:15]
	v_cmp_gt_f32_e32 vcc, s20, v46
	v_pk_mul_f32 v[4:5], v[4:5], v[220:221]
	v_pk_mul_f32 v[6:7], v[6:7], v[222:223]
	v_pk_fma_f32 v[6:7], v[6:7], v[238:239], v[74:75]
	v_pk_fma_f32 v[4:5], v[4:5], v[236:237], v[72:73]
	v_lshl_add_u64 v[20:21], v[34:35], 0, v[128:129]
	v_cvt_pk_bf16_f32 v4, v4, v5
	v_cvt_pk_bf16_f32 v5, v6, v7
	global_store_dwordx2 v[48:49], v[4:5], off offset:1536
	v_lshl_add_u64 v[24:25], v[32:33], 0, v[128:129]
	v_mul_f32_e32 v28, 0x4b800000, v46
	v_cndmask_b32_e32 v28, v46, v28, vcc
	v_rsq_f32_e32 v30, v28
	v_lshlrev_b64 v[28:29], 11, v[78:79]
	v_lshl_add_u64 v[28:29], v[70:71], 0, v[28:29]
	v_mul_f32_e32 v31, 0x45800000, v30
	v_cndmask_b32_e32 v30, v30, v31, vcc
	v_pk_mul_f32 v[18:19], v[18:19], v[30:31] op_sel_hi:[1,0]
	v_pk_mul_f32 v[16:17], v[16:17], v[30:31] op_sel_hi:[1,0]
	v_pk_mul_f32 v[14:15], v[14:15], v[30:31] op_sel_hi:[1,0]
	v_pk_mul_f32 v[12:13], v[12:13], v[30:31] op_sel_hi:[1,0]
	v_pk_mul_f32 v[10:11], v[10:11], v[30:31] op_sel_hi:[1,0]
	v_pk_mul_f32 v[8:9], v[8:9], v[30:31] op_sel_hi:[1,0]
	v_pk_mul_f32 v[2:3], v[2:3], v[30:31] op_sel_hi:[1,0]
	v_pk_mul_f32 v[0:1], v[0:1], v[30:31] op_sel_hi:[1,0]
	v_pk_mul_f32 v[4:5], v[16:17], v[208:209]
	v_pk_mul_f32 v[6:7], v[18:19], v[210:211]
	v_pk_fma_f32 v[6:7], v[6:7], v[226:227], v[242:243]
	v_pk_fma_f32 v[4:5], v[4:5], v[224:225], v[240:241]
	v_cvt_pk_bf16_f32 v4, v4, v5
	v_cvt_pk_bf16_f32 v5, v6, v7
	global_store_dwordx2 v[28:29], v[4:5], off
	v_pk_mul_f32 v[4:5], v[12:13], v[212:213]
	v_pk_mul_f32 v[6:7], v[14:15], v[214:215]
	v_pk_fma_f32 v[6:7], v[6:7], v[230:231], v[246:247]
	v_pk_fma_f32 v[4:5], v[4:5], v[228:229], v[244:245]
	v_cvt_pk_bf16_f32 v4, v4, v5
	v_cvt_pk_bf16_f32 v5, v6, v7
	global_store_dwordx2 v[28:29], v[4:5], off offset:512
	v_pk_mul_f32 v[4:5], v[8:9], v[216:217]
	v_pk_mul_f32 v[6:7], v[10:11], v[218:219]
	v_pk_fma_f32 v[6:7], v[6:7], v[234:235], v[110:111]
	v_pk_fma_f32 v[4:5], v[4:5], v[232:233], v[108:109]
	v_cvt_pk_bf16_f32 v4, v4, v5
	v_cvt_pk_bf16_f32 v5, v6, v7
	global_store_dwordx2 v[28:29], v[4:5], off offset:1024
	v_pk_mul_f32 v[0:1], v[0:1], v[220:221]
	v_pk_mul_f32 v[2:3], v[2:3], v[222:223]
	v_pk_fma_f32 v[2:3], v[2:3], v[238:239], v[74:75]
	v_pk_fma_f32 v[0:1], v[0:1], v[236:237], v[72:73]
	s_nop 0
	v_cvt_pk_bf16_f32 v0, v0, v1
	v_cvt_pk_bf16_f32 v1, v2, v3
	global_store_dwordx2 v[28:29], v[0:1], off offset:1536
	s_nop 0
	v_lshl_add_u32 v64, s4, 4, v64
	v_cmp_le_i32_e32 vcc, s22, v64
	s_or_b64 s[12:13], vcc, s[12:13]
	s_andn2_b64 exec, exec, s[12:13]
	s_cbranch_execz .LBB0_1907
